# gdn_prep step-2 decay-mask epilogue made branch-free (vector LDS reads of gc/beta, selects instead of 32 exec-masked blocks), on top of the LDS-DMA scan loop
# speedup vs baseline: 1.0642x; 1.0116x over previous
.LBB0_620:
	s_or_b64 exec, exec, s[0:1]
	v_ashrrev_i32_e32 v0, 2, v82
	s_cmp_eq_u32 s95, 0
	s_cselect_b64 vcc, -1, 0
	v_sub_u32_e32 v2, 63, v0
	v_cndmask_b32_e32 v2, v2, v0, vcc
	v_lshlrev_b32_e32 v3, 2, v2
	v_add_u32_e32 v4, 0x12100, v3
	s_waitcnt lgkmcnt(0)
	s_barrier
	ds_read_b32 v4, v4
	v_add_u32_e32 v5, 0x12200, v3
	ds_read_b32 v5, v5
	v_lshlrev_b32_e32 v7, 4, v82
	v_mul_lo_u32 v6, v2, s82
	v_and_b32_e32 v7, 48, v7
	v_add_u32_e32 v3, 0x12300, v3
	v_add_lshl_u32 v6, v6, v7, 1
	ds_read_b32 v3, v3
	ds_write_b128 v6, v[42:45] offset:9216
	ds_write_b128 v6, v[46:49] offset:9232
	ds_write_b128 v6, v[34:37]
	ds_write_b128 v6, v[38:41] offset:16
	s_waitcnt lgkmcnt(6)
	v_mul_f32_e32 v6, v4, v85
	s_waitcnt lgkmcnt(5)
	v_mul_f32_e32 v6, v5, v6
	v_mul_u32_u24_e32 v7, 0x48, v7
	v_cvt_pk_bf16_f32 v6, v6, s0
	v_add_lshl_u32 v2, v7, v2, 1
	ds_write_b16 v2, v6 offset:27648
	v_mul_f32_e32 v6, v4, v86
	v_mul_f32_e32 v6, v5, v6
	v_cvt_pk_bf16_f32 v6, v6, s0
	ds_write_b16 v2, v6 offset:27792
	s_waitcnt lgkmcnt(6)
	v_mul_f32_e32 v6, v3, v85
	v_cvt_pk_bf16_f32 v6, v6, s0
	ds_write_b16 v2, v6 offset:36864
	v_mul_f32_e32 v6, v3, v86
	v_cvt_pk_bf16_f32 v6, v6, s0
	ds_write_b16 v2, v6 offset:37008
	v_mul_f32_e32 v6, v4, v87
	v_cvt_pk_bf16_f32 v6, v6, s0
	ds_write_b16 v2, v6 offset:18432
	v_mul_f32_e32 v6, v4, v88
	v_cvt_pk_bf16_f32 v6, v6, s0
	ds_write_b16 v2, v6 offset:18576
	v_mul_f32_e32 v6, v4, v89
	v_mul_f32_e32 v6, v5, v6
	v_cvt_pk_bf16_f32 v6, v6, s0
	ds_write_b16 v2, v6 offset:27936
	v_mul_f32_e32 v6, v4, v90
	v_mul_f32_e32 v6, v5, v6
	v_cvt_pk_bf16_f32 v6, v6, s0
	ds_write_b16 v2, v6 offset:28080
	v_mul_f32_e32 v6, v3, v89
	v_cvt_pk_bf16_f32 v6, v6, s0
	ds_write_b16 v2, v6 offset:37152
	v_mul_f32_e32 v6, v3, v90
	v_cvt_pk_bf16_f32 v6, v6, s0
	ds_write_b16 v2, v6 offset:37296
	v_mul_f32_e32 v6, v4, v91
	v_cvt_pk_bf16_f32 v6, v6, s0
	ds_write_b16 v2, v6 offset:18720
	v_mul_f32_e32 v6, v4, v92
	v_cvt_pk_bf16_f32 v6, v6, s0
	ds_write_b16 v2, v6 offset:18864
	v_mul_f32_e32 v6, v4, v93
	v_mul_f32_e32 v6, v5, v6
	v_cvt_pk_bf16_f32 v6, v6, s0
	ds_write_b16 v2, v6 offset:28224
	v_mul_f32_e32 v6, v4, v94
	v_mul_f32_e32 v6, v5, v6
	v_cvt_pk_bf16_f32 v6, v6, s0
	ds_write_b16 v2, v6 offset:28368
	v_mul_f32_e32 v6, v3, v93
	v_cvt_pk_bf16_f32 v6, v6, s0
	ds_write_b16 v2, v6 offset:37440
	v_mul_f32_e32 v6, v3, v94
	v_cvt_pk_bf16_f32 v6, v6, s0
	ds_write_b16 v2, v6 offset:37584
	v_mul_f32_e32 v6, v4, v95
	v_cvt_pk_bf16_f32 v6, v6, s0
	ds_write_b16 v2, v6 offset:19008
	v_mul_f32_e32 v6, v4, v96
	v_cvt_pk_bf16_f32 v6, v6, s0
	ds_write_b16 v2, v6 offset:19152
	v_mul_f32_e32 v6, v4, v97
	v_mul_f32_e32 v6, v5, v6
	v_cvt_pk_bf16_f32 v6, v6, s0
	ds_write_b16 v2, v6 offset:28512
	v_mul_f32_e32 v6, v4, v98
	v_mul_f32_e32 v6, v5, v6
	v_cvt_pk_bf16_f32 v6, v6, s0
	ds_write_b16 v2, v6 offset:28656
	v_mul_f32_e32 v6, v3, v97
	v_cvt_pk_bf16_f32 v6, v6, s0
	ds_write_b16 v2, v6 offset:37728
	v_mul_f32_e32 v6, v3, v98
	v_cvt_pk_bf16_f32 v6, v6, s0
	ds_write_b16 v2, v6 offset:37872
	v_mul_f32_e32 v6, v4, v99
	v_cvt_pk_bf16_f32 v6, v6, s0
	ds_write_b16 v2, v6 offset:19296
	v_mul_f32_e32 v6, v4, v100
	v_cvt_pk_bf16_f32 v6, v6, s0
	ds_write_b16 v2, v6 offset:19440
	v_mul_f32_e32 v6, v4, v101
	v_mul_f32_e32 v6, v5, v6
	v_cvt_pk_bf16_f32 v6, v6, s0
	ds_write_b16 v2, v6 offset:28800
	v_mul_f32_e32 v6, v4, v102
	v_mul_f32_e32 v6, v5, v6
	v_cvt_pk_bf16_f32 v6, v6, s0
	ds_write_b16 v2, v6 offset:28944
	v_mul_f32_e32 v6, v3, v101
	v_cvt_pk_bf16_f32 v6, v6, s0
	ds_write_b16 v2, v6 offset:38016
	v_mul_f32_e32 v6, v3, v102
	v_cvt_pk_bf16_f32 v6, v6, s0
	ds_write_b16 v2, v6 offset:38160
	v_mul_f32_e32 v6, v4, v103
	v_cvt_pk_bf16_f32 v6, v6, s0
	ds_write_b16 v2, v6 offset:19584
	v_mul_f32_e32 v6, v4, v104
	v_cvt_pk_bf16_f32 v6, v6, s0
	ds_write_b16 v2, v6 offset:19728
	v_mul_f32_e32 v6, v4, v105
	v_mul_f32_e32 v6, v5, v6
	v_cvt_pk_bf16_f32 v6, v6, s0
	ds_write_b16 v2, v6 offset:29088
	v_mul_f32_e32 v6, v4, v106
	v_mul_f32_e32 v6, v5, v6
	v_cvt_pk_bf16_f32 v6, v6, s0
	ds_write_b16 v2, v6 offset:29232
	v_mul_f32_e32 v6, v3, v105
	v_cvt_pk_bf16_f32 v6, v6, s0
	ds_write_b16 v2, v6 offset:38304
	v_mul_f32_e32 v6, v3, v106
	v_cvt_pk_bf16_f32 v6, v6, s0
	ds_write_b16 v2, v6 offset:38448
	v_mul_f32_e32 v6, v4, v107
	v_cvt_pk_bf16_f32 v6, v6, s0
	ds_write_b16 v2, v6 offset:19872
	v_mul_f32_e32 v6, v4, v108
	v_cvt_pk_bf16_f32 v6, v6, s0
	ds_write_b16 v2, v6 offset:20016
	v_mul_f32_e32 v6, v4, v109
	v_mul_f32_e32 v6, v5, v6
	v_cvt_pk_bf16_f32 v6, v6, s0
	ds_write_b16 v2, v6 offset:29376
	v_mul_f32_e32 v6, v4, v110
	v_mul_f32_e32 v6, v5, v6
	v_cvt_pk_bf16_f32 v6, v6, s0
	ds_write_b16 v2, v6 offset:29520
	v_mul_f32_e32 v6, v3, v109
	v_cvt_pk_bf16_f32 v6, v6, s0
	ds_write_b16 v2, v6 offset:38592
	v_mul_f32_e32 v6, v3, v110
	v_cvt_pk_bf16_f32 v6, v6, s0
	ds_write_b16 v2, v6 offset:38736
	v_mul_f32_e32 v6, v4, v111
	v_cvt_pk_bf16_f32 v6, v6, s0
	ds_write_b16 v2, v6 offset:20160
	v_mul_f32_e32 v6, v4, v112
	v_cvt_pk_bf16_f32 v6, v6, s0
	ds_write_b16 v2, v6 offset:20304
	v_mul_f32_e32 v6, v4, v113
	v_mul_f32_e32 v6, v5, v6
	v_cvt_pk_bf16_f32 v6, v6, s0
	ds_write_b16 v2, v6 offset:29664
	v_mul_f32_e32 v6, v4, v114
	v_mul_f32_e32 v5, v5, v6
	v_cvt_pk_bf16_f32 v5, v5, s0
	ds_write_b16 v2, v5 offset:29808
	v_mul_f32_e32 v5, v3, v113
	v_mul_f32_e32 v3, v3, v114
	v_cvt_pk_bf16_f32 v3, v3, s0
	ds_write_b16 v2, v3 offset:39024
	v_mul_f32_e32 v3, v4, v115
	v_cvt_pk_bf16_f32 v3, v3, s0
	ds_write_b16 v2, v3 offset:20448
	v_mul_f32_e32 v3, v4, v116
	v_bfe_u32 v54, v82, 5, 1
	v_cvt_pk_bf16_f32 v5, v5, s0
	v_cvt_pk_bf16_f32 v3, v3, s0
	s_movk_i32 s0, 0xffe0
	v_and_b32_e32 v126, 31, v82
	ds_write_b16 v2, v5 offset:38880
	ds_write_b16 v2, v3 offset:20592
	v_bfe_u32 v124, v82, 6, 1
	v_and_b32_e32 v52, 0xffffffe0, v0
	v_bfi_b32 v0, s0, v0, v82
	v_lshlrev_b32_e32 v2, 4, v54
	v_mad_u64_u32 v[50:51], s[0:1], v0, s72, v[2:3]
	v_lshl_or_b32 v0, v124, 5, v126
	v_mul_u32_u24_e32 v3, 0x48, v0
	v_lshlrev_b32_e32 v134, 1, v3
	s_waitcnt lgkmcnt(0)
	s_barrier
	v_add_u32_e32 v125, v134, v2
	ds_read_b128 v[2:5], v50
	ds_read_b128 v[18:21], v50 offset:32
	ds_read_b128 v[22:25], v125
	ds_read_b128 v[56:59], v125 offset:32
	s_waitcnt lgkmcnt(1)
	v_mfma_f32_32x32x16_bf16 v[2:17], v[2:5], v[22:25], 0
	v_lshl_or_b32 v51, v0, 2, v189
	v_lshl_or_b32 v140, v54, 2, v52
	v_cmp_ge_i32_e64 s[0:1], v140, v0
	v_mov_b32_e32 v55, 0
	s_waitcnt lgkmcnt(0)
	v_mfma_f32_32x32x16_bf16 v[2:17], v[18:21], v[56:59], v[2:17]
	ds_read_b128 v[18:21], v50 offset:64
	ds_read_b128 v[60:63], v125 offset:64
	s_waitcnt lgkmcnt(0)
	v_mfma_f32_32x32x16_bf16 v[2:17], v[18:21], v[60:63], v[2:17]
	ds_read_b128 v[18:21], v50 offset:96
	ds_read_b128 v[64:67], v125 offset:96
	ds_read_b128 v[68:71], v50 offset:9248
	ds_read_b32 v51, v51
	s_waitcnt lgkmcnt(2)
	v_mfma_f32_32x32x16_bf16 v[2:17], v[18:21], v[64:67], v[2:17]
	ds_read_b128 v[18:21], v50 offset:9216
	s_waitcnt lgkmcnt(0)
	v_mfma_f32_32x32x16_bf16 v[18:33], v[18:21], v[22:25], 0
	v_mfma_f32_32x32x16_bf16 v[18:33], v[68:71], v[56:59], v[18:33]
	ds_read_b128 v[56:59], v50 offset:9280
	s_waitcnt lgkmcnt(0)
	v_mfma_f32_32x32x16_bf16 v[18:33], v[56:59], v[60:63], v[18:33]
	ds_read_b128 v[56:59], v50 offset:9312
	s_waitcnt lgkmcnt(0)
	v_mfma_f32_32x32x16_bf16 v[18:33], v[56:59], v[64:67], v[18:33]
	v_mad_u64_u32 v[132:133], s[22:23], v140, s82, v[0:1]
	v_sub_u32_e32 v57, v0, v140
	v_lshlrev_b32_e32 v127, 2, v132
	v_lshl_add_u32 v135, v140, 2, v194
	v_lshl_add_u32 v133, v140, 2, v189
	v_lshlrev_b32_e32 v132, 1, v132
	ds_read_b128 v[128:131], v133 offset:0
	ds_read_b128 v[136:139], v135 offset:0
	s_waitcnt lgkmcnt(0)
	v_sub_f32_e32 v128, v128, v51
	v_mul_f32_e32 v128, 0x3fb8aa3b, v128
	v_exp_f32_e32 v128, v128
	v_mul_f32_e32 v2, v2, v136
	v_cmp_ge_i32_e64 s[0:1], 0, v57
	v_cndmask_b32_e64 v128, 0, v128, s[0:1]
	v_mul_f32_e32 v2, v128, v2
	v_cmp_gt_i32_e64 s[0:1], 0, v57
	v_cndmask_b32_e64 v2, 0, v2, s[0:1]
	ds_write_b32 v127, v2 offset:55296
	v_mul_f32_e32 v18, v18, v128
	v_cvt_pk_bf16_f32 v18, v18, v18
	ds_write_b16 v132, v18 offset:46080
	v_sub_f32_e32 v129, v129, v51
	v_mul_f32_e32 v129, 0x3fb8aa3b, v129
	v_exp_f32_e32 v129, v129
	v_mul_f32_e32 v3, v3, v137
	v_cmp_ge_i32_e64 s[0:1], 1, v57
	v_cndmask_b32_e64 v129, 0, v129, s[0:1]
	v_mul_f32_e32 v3, v129, v3
	v_cmp_gt_i32_e64 s[0:1], 1, v57
	v_cndmask_b32_e64 v3, 0, v3, s[0:1]
	ds_write_b32 v127, v3 offset:55584
	v_mul_f32_e32 v19, v19, v129
	v_cvt_pk_bf16_f32 v19, v19, v19
	ds_write_b16 v132, v19 offset:46224
	v_sub_f32_e32 v130, v130, v51
	v_mul_f32_e32 v130, 0x3fb8aa3b, v130
	v_exp_f32_e32 v130, v130
	v_mul_f32_e32 v4, v4, v138
	v_cmp_ge_i32_e64 s[0:1], 2, v57
	v_cndmask_b32_e64 v130, 0, v130, s[0:1]
	v_mul_f32_e32 v4, v130, v4
	v_cmp_gt_i32_e64 s[0:1], 2, v57
	v_cndmask_b32_e64 v4, 0, v4, s[0:1]
	ds_write_b32 v127, v4 offset:55872
	v_mul_f32_e32 v20, v20, v130
	v_cvt_pk_bf16_f32 v20, v20, v20
	ds_write_b16 v132, v20 offset:46368
	v_sub_f32_e32 v131, v131, v51
	v_mul_f32_e32 v131, 0x3fb8aa3b, v131
	v_exp_f32_e32 v131, v131
	v_mul_f32_e32 v5, v5, v139
	v_cmp_ge_i32_e64 s[0:1], 3, v57
	v_cndmask_b32_e64 v131, 0, v131, s[0:1]
	v_mul_f32_e32 v5, v131, v5
	v_cmp_gt_i32_e64 s[0:1], 3, v57
	v_cndmask_b32_e64 v5, 0, v5, s[0:1]
	ds_write_b32 v127, v5 offset:56160
	v_mul_f32_e32 v21, v21, v131
	v_cvt_pk_bf16_f32 v21, v21, v21
	ds_write_b16 v132, v21 offset:46512
	ds_read_b128 v[2:5], v133 offset:32
	ds_read_b128 v[18:21], v135 offset:32
	ds_read_b128 v[128:131], v133 offset:64
	ds_read_b128 v[136:139], v135 offset:64
	s_waitcnt lgkmcnt(2)
	v_sub_f32_e32 v2, v2, v51
	v_mul_f32_e32 v2, 0x3fb8aa3b, v2
	v_exp_f32_e32 v2, v2
	v_mul_f32_e32 v6, v6, v18
	v_cmp_ge_i32_e64 s[0:1], 8, v57
	v_cndmask_b32_e64 v2, 0, v2, s[0:1]
	v_mul_f32_e32 v6, v2, v6
	v_cmp_gt_i32_e64 s[0:1], 8, v57
	v_cndmask_b32_e64 v6, 0, v6, s[0:1]
	ds_write_b32 v127, v6 offset:57600
	v_mul_f32_e32 v22, v22, v2
	v_cvt_pk_bf16_f32 v22, v22, v22
	ds_write_b16 v132, v22 offset:47232
	v_sub_f32_e32 v3, v3, v51
	v_mul_f32_e32 v3, 0x3fb8aa3b, v3
	v_exp_f32_e32 v3, v3
	v_mul_f32_e32 v7, v7, v19
	v_cmp_ge_i32_e64 s[0:1], 9, v57
	v_cndmask_b32_e64 v3, 0, v3, s[0:1]
	v_mul_f32_e32 v7, v3, v7
	v_cmp_gt_i32_e64 s[0:1], 9, v57
	v_cndmask_b32_e64 v7, 0, v7, s[0:1]
	ds_write_b32 v127, v7 offset:57888
	v_mul_f32_e32 v23, v23, v3
	v_cvt_pk_bf16_f32 v23, v23, v23
	ds_write_b16 v132, v23 offset:47376
	v_sub_f32_e32 v4, v4, v51
	v_mul_f32_e32 v4, 0x3fb8aa3b, v4
	v_exp_f32_e32 v4, v4
	v_mul_f32_e32 v8, v8, v20
	v_cmp_ge_i32_e64 s[0:1], 10, v57
	v_cndmask_b32_e64 v4, 0, v4, s[0:1]
	v_mul_f32_e32 v8, v4, v8
	v_cmp_gt_i32_e64 s[0:1], 10, v57
	v_cndmask_b32_e64 v8, 0, v8, s[0:1]
	ds_write_b32 v127, v8 offset:58176
	v_mul_f32_e32 v24, v24, v4
	v_cvt_pk_bf16_f32 v24, v24, v24
	ds_write_b16 v132, v24 offset:47520
	v_sub_f32_e32 v5, v5, v51
	v_mul_f32_e32 v5, 0x3fb8aa3b, v5
	v_exp_f32_e32 v5, v5
	v_mul_f32_e32 v9, v9, v21
	v_cmp_ge_i32_e64 s[0:1], 11, v57
	v_cndmask_b32_e64 v5, 0, v5, s[0:1]
	v_mul_f32_e32 v9, v5, v9
	v_cmp_gt_i32_e64 s[0:1], 11, v57
	v_cndmask_b32_e64 v9, 0, v9, s[0:1]
	ds_write_b32 v127, v9 offset:58464
	v_mul_f32_e32 v25, v25, v5
	v_cvt_pk_bf16_f32 v25, v25, v25
	ds_write_b16 v132, v25 offset:47664
	ds_read_b128 v[6:9], v133 offset:96
	ds_read_b128 v[22:25], v135 offset:96
	s_waitcnt lgkmcnt(10)
	v_sub_f32_e32 v128, v128, v51
	v_mul_f32_e32 v128, 0x3fb8aa3b, v128
	v_exp_f32_e32 v128, v128
	v_mul_f32_e32 v10, v10, v136
	v_cmp_ge_i32_e64 s[0:1], 16, v57
	v_cndmask_b32_e64 v128, 0, v128, s[0:1]
	v_mul_f32_e32 v10, v128, v10
	v_cmp_gt_i32_e64 s[0:1], 16, v57
	v_cndmask_b32_e64 v10, 0, v10, s[0:1]
	ds_write_b32 v127, v10 offset:59904
	v_mul_f32_e32 v26, v26, v128
	v_cvt_pk_bf16_f32 v26, v26, v26
	ds_write_b16 v132, v26 offset:48384
	v_sub_f32_e32 v129, v129, v51
	v_mul_f32_e32 v129, 0x3fb8aa3b, v129
	v_exp_f32_e32 v129, v129
	v_mul_f32_e32 v11, v11, v137
	v_cmp_ge_i32_e64 s[0:1], 17, v57
	v_cndmask_b32_e64 v129, 0, v129, s[0:1]
	v_mul_f32_e32 v11, v129, v11
	v_cmp_gt_i32_e64 s[0:1], 17, v57
	v_cndmask_b32_e64 v11, 0, v11, s[0:1]
	ds_write_b32 v127, v11 offset:60192
	v_mul_f32_e32 v27, v27, v129
	v_cvt_pk_bf16_f32 v27, v27, v27
	ds_write_b16 v132, v27 offset:48528
	v_sub_f32_e32 v130, v130, v51
	v_mul_f32_e32 v130, 0x3fb8aa3b, v130
	v_exp_f32_e32 v130, v130
	v_mul_f32_e32 v12, v12, v138
	v_cmp_ge_i32_e64 s[0:1], 18, v57
	v_cndmask_b32_e64 v130, 0, v130, s[0:1]
	v_mul_f32_e32 v12, v130, v12
	v_cmp_gt_i32_e64 s[0:1], 18, v57
	v_cndmask_b32_e64 v12, 0, v12, s[0:1]
	ds_write_b32 v127, v12 offset:60480
	v_mul_f32_e32 v28, v28, v130
	v_cvt_pk_bf16_f32 v28, v28, v28
	ds_write_b16 v132, v28 offset:48672
	v_sub_f32_e32 v131, v131, v51
	v_mul_f32_e32 v131, 0x3fb8aa3b, v131
	v_exp_f32_e32 v131, v131
	v_mul_f32_e32 v13, v13, v139
	v_cmp_ge_i32_e64 s[0:1], 19, v57
	v_cndmask_b32_e64 v131, 0, v131, s[0:1]
	v_mul_f32_e32 v13, v131, v13
	v_cmp_gt_i32_e64 s[0:1], 19, v57
	v_cndmask_b32_e64 v13, 0, v13, s[0:1]
	ds_write_b32 v127, v13 offset:60768
	v_mul_f32_e32 v29, v29, v131
	v_cvt_pk_bf16_f32 v29, v29, v29
	ds_write_b16 v132, v29 offset:48816
	s_waitcnt lgkmcnt(8)
	v_sub_f32_e32 v6, v6, v51
	v_mul_f32_e32 v6, 0x3fb8aa3b, v6
	v_exp_f32_e32 v6, v6
	v_mul_f32_e32 v14, v14, v22
	v_cmp_ge_i32_e64 s[0:1], 24, v57
	v_cndmask_b32_e64 v6, 0, v6, s[0:1]
	v_mul_f32_e32 v14, v6, v14
	v_cmp_gt_i32_e64 s[0:1], 24, v57
	v_cndmask_b32_e64 v14, 0, v14, s[0:1]
	ds_write_b32 v127, v14 offset:62208
	v_mul_f32_e32 v30, v30, v6
	v_cvt_pk_bf16_f32 v30, v30, v30
	ds_write_b16 v132, v30 offset:49536
	v_sub_f32_e32 v7, v7, v51
	v_mul_f32_e32 v7, 0x3fb8aa3b, v7
	v_exp_f32_e32 v7, v7
	v_mul_f32_e32 v15, v15, v23
	v_cmp_ge_i32_e64 s[0:1], 25, v57
	v_cndmask_b32_e64 v7, 0, v7, s[0:1]
	v_mul_f32_e32 v15, v7, v15
	v_cmp_gt_i32_e64 s[0:1], 25, v57
	v_cndmask_b32_e64 v15, 0, v15, s[0:1]
	ds_write_b32 v127, v15 offset:62496
	v_mul_f32_e32 v31, v31, v7
	v_cvt_pk_bf16_f32 v31, v31, v31
	ds_write_b16 v132, v31 offset:49680
	v_sub_f32_e32 v8, v8, v51
	v_mul_f32_e32 v8, 0x3fb8aa3b, v8
	v_exp_f32_e32 v8, v8
	v_mul_f32_e32 v16, v16, v24
	v_cmp_ge_i32_e64 s[0:1], 26, v57
	v_cndmask_b32_e64 v8, 0, v8, s[0:1]
	v_mul_f32_e32 v16, v8, v16
	v_cmp_gt_i32_e64 s[0:1], 26, v57
	v_cndmask_b32_e64 v16, 0, v16, s[0:1]
	ds_write_b32 v127, v16 offset:62784
	v_mul_f32_e32 v32, v32, v8
	v_cvt_pk_bf16_f32 v32, v32, v32
	ds_write_b16 v132, v32 offset:49824
	v_sub_f32_e32 v9, v9, v51
	v_mul_f32_e32 v9, 0x3fb8aa3b, v9
	v_exp_f32_e32 v9, v9
	v_mul_f32_e32 v17, v17, v25
	v_cmp_ge_i32_e64 s[0:1], 27, v57
	v_cndmask_b32_e64 v9, 0, v9, s[0:1]
	v_mul_f32_e32 v17, v9, v17
	v_cmp_gt_i32_e64 s[0:1], 27, v57
	v_cndmask_b32_e64 v17, 0, v17, s[0:1]
	ds_write_b32 v127, v17 offset:63072
	v_mul_f32_e32 v33, v33, v9
	v_cvt_pk_bf16_f32 v33, v33, v33
	ds_write_b16 v132, v33 offset:49968
	v_or_b32_e32 v138, 1, v140
	v_or_b32_e32 v136, 2, v140
	v_or_b32_e32 v133, 3, v140
	v_or_b32_e32 v131, 8, v140
	v_or_b32_e32 v129, 9, v140
	v_or_b32_e32 v127, 10, v140
	v_or_b32_e32 v130, 11, v140
	v_or_b32_e32 v132, 16, v140
	v_or_b32_e32 v135, 17, v140
	v_or_b32_e32 v137, 18, v140
	v_or_b32_e32 v139, 19, v140
	v_or_b32_e32 v141, 24, v140
	v_or_b32_e32 v142, 25, v140
	v_or_b32_e32 v143, 26, v140
	v_or_b32_e32 v128, 27, v140
	v_cmp_gt_u32_e64 s[38:39], 64, v82
	v_and_b32_e32 v2, 15, v82
	s_waitcnt lgkmcnt(0)
	s_barrier
	s_and_saveexec_b64 s[40:41], s[38:39]
	s_cbranch_execz .LBB0_686
	v_and_b32_e32 v3, 48, v82
	v_lshlrev_b32_e32 v19, 2, v3
	v_mul_u32_u24_e32 v3, 0x120, v3
	v_or_b32_e32 v15, v19, v3
	ds_read_b32 v9, v15 offset:55584
	v_cmp_eq_u32_e64 s[0:1], 0, v2
	ds_read_b64 v[4:5], v15 offset:55872
	ds_read_b96 v[6:8], v15 offset:56160
	v_cndmask_b32_e64 v20, 0, 1.0, s[0:1]
	v_cmp_eq_u32_e64 s[0:1], 1, v2
	s_nop 1
	v_cndmask_b32_e64 v10, 0, 1.0, s[0:1]
	v_cmp_eq_u32_e64 s[0:1], 2, v2
	s_waitcnt lgkmcnt(2)
	v_fma_f32 v21, -v20, v9, v10
	v_cndmask_b32_e64 v9, 0, 1.0, s[0:1]
	s_waitcnt lgkmcnt(1)
	v_fma_f32 v4, -v20, v4, v9
	v_cmp_eq_u32_e64 s[0:1], 3, v2
	v_fma_f32 v22, -v5, v21, v4
	s_nop 0
	v_cndmask_b32_e64 v4, 0, 1.0, s[0:1]
	s_waitcnt lgkmcnt(0)
	v_fma_f32 v4, -v20, v6, v4
	v_fma_f32 v9, -v21, v7, v4
	ds_read_b128 v[4:7], v15 offset:56448
	v_cmp_eq_u32_e64 s[0:1], 4, v2
	v_fma_f32 v23, -v22, v8, v9
	ds_read_b128 v[8:11], v15 offset:56736
	v_cndmask_b32_e64 v12, 0, 1.0, s[0:1]
	s_waitcnt lgkmcnt(1)
	v_fma_f32 v4, -v20, v4, v12
	v_fma_f32 v4, -v21, v5, v4
	v_fma_f32 v4, -v22, v6, v4
	v_cmp_eq_u32_e64 s[0:1], 5, v2
	v_fma_f32 v24, -v23, v7, v4
	s_nop 0
	v_cndmask_b32_e64 v4, 0, 1.0, s[0:1]
	s_waitcnt lgkmcnt(0)
	v_fma_f32 v4, -v20, v8, v4
	ds_read_b32 v8, v15 offset:56752
	v_fma_f32 v4, -v21, v9, v4
	v_fma_f32 v9, -v22, v10, v4
	ds_read_b128 v[4:7], v15 offset:57024
	v_fma_f32 v9, -v23, v11, v9
	v_cmp_eq_u32_e64 s[0:1], 6, v2
	s_waitcnt lgkmcnt(1)
	v_fma_f32 v25, -v24, v8, v9
	v_cndmask_b32_e64 v8, 0, 1.0, s[0:1]
	s_waitcnt lgkmcnt(0)
	v_fma_f32 v4, -v20, v4, v8
	ds_read_b64 v[8:9], v15 offset:57040
	v_fma_f32 v4, -v21, v5, v4
	v_fma_f32 v4, -v22, v6, v4
	v_fma_f32 v10, -v23, v7, v4
	ds_read_b128 v[4:7], v15 offset:57312
	s_waitcnt lgkmcnt(1)
	v_fma_f32 v8, -v24, v8, v10
	v_cmp_eq_u32_e64 s[0:1], 7, v2
	v_fma_f32 v26, -v25, v9, v8
	s_nop 0
	v_cndmask_b32_e64 v8, 0, 1.0, s[0:1]
	s_waitcnt lgkmcnt(0)
	v_fma_f32 v4, -v20, v4, v8
	ds_read_b96 v[8:10], v15 offset:57328
	v_fma_f32 v4, -v21, v5, v4
	v_fma_f32 v4, -v22, v6, v4
	v_fma_f32 v11, -v23, v7, v4
	ds_read_b128 v[4:7], v15 offset:57600
	s_waitcnt lgkmcnt(1)
	v_fma_f32 v8, -v24, v8, v11
	v_fma_f32 v8, -v25, v9, v8
	v_cmp_eq_u32_e64 s[0:1], 8, v2
	v_fma_f32 v27, -v26, v10, v8
	s_nop 0
	v_cndmask_b32_e64 v8, 0, 1.0, s[0:1]
	s_waitcnt lgkmcnt(0)
	v_fma_f32 v4, -v20, v4, v8
	ds_read_b128 v[8:11], v15 offset:57616
	v_fma_f32 v4, -v21, v5, v4
	v_fma_f32 v4, -v22, v6, v4
	v_fma_f32 v12, -v23, v7, v4
	ds_read_b128 v[4:7], v15 offset:57888
	s_waitcnt lgkmcnt(1)
	v_fma_f32 v8, -v24, v8, v12
	v_fma_f32 v8, -v25, v9, v8
	v_fma_f32 v8, -v26, v10, v8
	v_cmp_eq_u32_e64 s[0:1], 9, v2
	v_fma_f32 v28, -v27, v11, v8
	ds_read_b32 v12, v15 offset:57920
	v_cndmask_b32_e64 v8, 0, 1.0, s[0:1]
	s_waitcnt lgkmcnt(1)
	v_fma_f32 v4, -v20, v4, v8
	ds_read_b128 v[8:11], v15 offset:57904
	v_fma_f32 v4, -v21, v5, v4
	v_fma_f32 v4, -v22, v6, v4
	v_fma_f32 v4, -v23, v7, v4
	v_cmp_eq_u32_e64 s[0:1], 10, v2
	s_waitcnt lgkmcnt(0)
	v_fma_f32 v4, -v24, v8, v4
	v_fma_f32 v4, -v25, v9, v4
	v_fma_f32 v4, -v26, v10, v4
	v_fma_f32 v8, -v27, v11, v4
	ds_read_b128 v[4:7], v15 offset:58176
	v_fma_f32 v29, -v28, v12, v8
	v_cndmask_b32_e64 v12, 0, 1.0, s[0:1]
	ds_read_b128 v[8:11], v15 offset:58192
	v_cmp_eq_u32_e64 s[0:1], 11, v2
	s_waitcnt lgkmcnt(1)
	v_fma_f32 v4, -v20, v4, v12
	v_fma_f32 v4, -v21, v5, v4
	v_fma_f32 v4, -v22, v6, v4
	v_fma_f32 v4, -v23, v7, v4
	s_waitcnt lgkmcnt(0)
	v_fma_f32 v4, -v24, v8, v4
	ds_read_b64 v[12:13], v15 offset:58208
	v_fma_f32 v4, -v25, v9, v4
	v_fma_f32 v4, -v26, v10, v4
	v_fma_f32 v8, -v27, v11, v4
	ds_read_b128 v[4:7], v15 offset:58464
	s_waitcnt lgkmcnt(1)
	v_fma_f32 v8, -v28, v12, v8
	v_fma_f32 v30, -v29, v13, v8
	v_cndmask_b32_e64 v8, 0, 1.0, s[0:1]
	ds_read_b96 v[12:14], v15 offset:58496
	s_waitcnt lgkmcnt(1)
	v_fma_f32 v4, -v20, v4, v8
	ds_read_b128 v[8:11], v15 offset:58480
	v_fma_f32 v4, -v21, v5, v4
	v_fma_f32 v4, -v22, v6, v4
	v_fma_f32 v4, -v23, v7, v4
	v_cmp_eq_u32_e64 s[0:1], 12, v2
	s_waitcnt lgkmcnt(0)
	v_fma_f32 v4, -v24, v8, v4
	v_fma_f32 v4, -v25, v9, v4
	v_fma_f32 v4, -v26, v10, v4
	v_fma_f32 v4, -v27, v11, v4
	v_fma_f32 v4, -v28, v12, v4
	v_fma_f32 v8, -v29, v13, v4
	ds_read_b128 v[4:7], v15 offset:58752
	v_fma_f32 v31, -v30, v14, v8
	v_cndmask_b32_e64 v12, 0, 1.0, s[0:1]
	ds_read_b128 v[8:11], v15 offset:58768
	v_cmp_eq_u32_e64 s[0:1], 13, v2
	s_waitcnt lgkmcnt(1)
	v_fma_f32 v4, -v20, v4, v12
	v_fma_f32 v4, -v21, v5, v4
	v_fma_f32 v4, -v22, v6, v4
	v_fma_f32 v4, -v23, v7, v4
	s_waitcnt lgkmcnt(0)
	v_fma_f32 v8, -v24, v8, v4
	ds_read_b128 v[4:7], v15 offset:58784
	v_fma_f32 v8, -v25, v9, v8
	v_fma_f32 v8, -v26, v10, v8
	v_fma_f32 v12, -v27, v11, v8
	ds_read_b128 v[8:11], v15 offset:59040
	s_waitcnt lgkmcnt(1)
	v_fma_f32 v4, -v28, v4, v12
	v_fma_f32 v4, -v29, v5, v4
	v_fma_f32 v4, -v30, v6, v4
	v_fma_f32 v32, -v31, v7, v4
	v_cndmask_b32_e64 v4, 0, 1.0, s[0:1]
	s_waitcnt lgkmcnt(0)
	v_fma_f32 v8, -v20, v8, v4
	ds_read_b128 v[4:7], v15 offset:59056
	v_fma_f32 v8, -v21, v9, v8
	v_fma_f32 v8, -v22, v10, v8
	v_fma_f32 v12, -v23, v11, v8
	ds_read_b128 v[8:11], v15 offset:59072
	s_waitcnt lgkmcnt(1)
	v_fma_f32 v4, -v24, v4, v12
	v_fma_f32 v4, -v25, v5, v4
	v_fma_f32 v4, -v26, v6, v4
	v_fma_f32 v4, -v27, v7, v4
	s_waitcnt lgkmcnt(0)
	v_fma_f32 v4, -v28, v8, v4
	ds_read_b32 v8, v15 offset:59088
	v_fma_f32 v4, -v29, v9, v4
	v_fma_f32 v9, -v30, v10, v4
	ds_read_b128 v[4:7], v15 offset:59328
	v_fma_f32 v9, -v31, v11, v9
	v_cmp_eq_u32_e64 s[0:1], 14, v2
	s_waitcnt lgkmcnt(1)
	v_fma_f32 v33, -v32, v8, v9
	v_cndmask_b32_e64 v8, 0, 1.0, s[0:1]
	s_waitcnt lgkmcnt(0)
	v_fma_f32 v4, -v20, v4, v8
	ds_read_b128 v[8:11], v15 offset:59344
	v_fma_f32 v4, -v21, v5, v4
	v_fma_f32 v4, -v22, v6, v4
	v_fma_f32 v12, -v23, v7, v4
	ds_read_b128 v[4:7], v15 offset:59360
	s_waitcnt lgkmcnt(1)
	v_fma_f32 v8, -v24, v8, v12
	v_fma_f32 v8, -v25, v9, v8
	v_fma_f32 v8, -v26, v10, v8
	v_fma_f32 v8, -v27, v11, v8
	s_waitcnt lgkmcnt(0)
	v_fma_f32 v4, -v28, v4, v8
	v_fma_f32 v4, -v29, v5, v4
	v_fma_f32 v4, -v30, v6, v4
	v_fma_f32 v10, -v31, v7, v4
	v_or_b32_e32 v4, 15, v82
	v_mul_lo_u32 v51, v4, s54
	v_add_u32_e32 v16, v19, v51
	ds_read_b64 v[8:9], v15 offset:59376
	ds_read_b128 v[4:7], v16 offset:55296
	v_cmp_eq_u32_e64 s[0:1], 15, v2
	s_waitcnt lgkmcnt(1)
	v_fma_f32 v8, -v32, v8, v10
	v_cndmask_b32_e64 v53, 0, 1.0, s[0:1]
	s_waitcnt lgkmcnt(0)
	v_fma_f32 v4, -v20, v4, v53
	v_fma_f32 v52, -v33, v9, v8
	ds_read_b128 v[8:11], v16 offset:55312
	ds_read_b128 v[12:15], v16 offset:55328
	ds_read_b96 v[16:18], v16 offset:55344
	v_fma_f32 v4, -v21, v5, v4
	v_fma_f32 v4, -v22, v6, v4
	v_fma_f32 v4, -v23, v7, v4
	s_waitcnt lgkmcnt(2)
	v_fma_f32 v4, -v24, v8, v4
	v_fma_f32 v4, -v25, v9, v4
	v_fma_f32 v4, -v26, v10, v4
	v_fma_f32 v4, -v27, v11, v4
	v_lshl_or_b32 v5, v2, 2, v19
	s_waitcnt lgkmcnt(1)
	v_fma_f32 v4, -v28, v12, v4
	v_or_b32_e32 v3, v5, v3
	v_fma_f32 v4, -v29, v13, v4
	v_add_u32_e32 v6, 0xd800, v3
	v_fma_f32 v4, -v30, v14, v4
	ds_write2_b32 v6, v20, v21 offset1:72
	ds_write2_b32 v6, v22, v23 offset0:144 offset1:216
	v_add_u32_e32 v6, 0xdc00, v3
	v_fma_f32 v4, -v31, v15, v4
	ds_write2_b32 v6, v24, v25 offset0:32 offset1:104
	ds_write2_b32 v6, v26, v27 offset0:176 offset1:248
	v_add_u32_e32 v6, 0xe000, v3
	s_waitcnt lgkmcnt(4)
	v_fma_f32 v4, -v32, v16, v4
	ds_write2_b32 v6, v28, v29 offset0:64 offset1:136
	v_add_u32_e32 v6, 0xe200, v3
	v_fma_f32 v4, -v33, v17, v4
	ds_write2_b32 v6, v30, v31 offset0:80 offset1:152
	v_add_u32_e32 v6, 0xe400, v3
	v_fma_f32 v4, -v52, v18, v4
	ds_write2_b32 v6, v32, v33 offset0:96 offset1:168
	ds_write_b32 v3, v52 offset:59328
	v_add_u32_e32 v3, v5, v51
	ds_write_b32 v3, v4 offset:55296
